# P4 chain loop rebuilt with per-step descriptor/address tables read by v_readlane (no per-step scalar index math / SGPR rotation); compute blocks unchanged
# speedup vs baseline: 1.0425x; 1.0086x over previous
.Lp4n_entry:
	s_and_b32 s45, s96, 7
	s_lshr_b32 s46, s96, 3
	s_cmp_lt_u32 s46, 16
	s_cbranch_scc0 .Lp4n_ctx
	s_lshr_b32 s47, s46, 2
	s_lshl_b32 s48, s45, 2
	s_add_u32 s47, s48, s47
	s_and_b32 s57, s46, 3
	s_lshr_b32 s58, s47, 4
	s_bfe_u32 s59, s47, 0x30001
	s_and_b32 s60, s47, 1
	s_mov_b32 s61, 63
	s_mov_b32 s62, 6
	s_mov_b32 s63, 1
	s_lshl_b32 s64, s58, 6
	s_add_u32 s64, s64, 0x80
	s_lshl_b32 s65, s58, 12
	s_add_u32 s65, s65, 0x2000
	s_add_u32 s66, s65, 0x1000
	s_branch .Lp4n_tab
.Lp4n_ctx:
	s_sub_u32 s46, s46, 16
	s_lshr_b32 s47, s46, 2
	s_lshl_b32 s48, s45, 2
	s_add_u32 s58, s48, s47
	s_and_b32 s57, s46, 3
	s_mov_b32 s59, 0
	s_mov_b32 s60, 0
	s_mov_b32 s61, 3
	s_mov_b32 s62, 2
	s_mov_b32 s63, 0
	s_lshl_b32 s64, s58, 2
	s_lshl_b32 s65, s58, 8
	s_add_u32 s66, s65, 0x100
.Lp4n_tab:
	v_mbcnt_lo_u32_b32 v229, -1, 0
	v_mbcnt_hi_u32_b32 v229, -1, v229
	v_and_b32_e32 v230, s61, v229
	v_lshrrev_b32_e32 v231, s62, v229
	v_lshrrev_b32_e32 v232, 1, v231
	v_add_u32_e32 v232, s59, v232
	v_and_b32_e32 v232, 7, v232
	v_add_u32_e32 v233, s60, v231
	v_and_b32_e32 v233, 1, v233
	v_sub_u32_e32 v234, s61, v230
	v_cmp_eq_u32_e32 vcc, 1, v233
	s_nop 1
	v_cndmask_b32_e32 v235, v230, v234, vcc
	v_add_u32_e32 v235, s64, v235
	v_cmp_eq_u32_e32 vcc, s61, v230
	s_nop 1
	v_cndmask_b32_e64 v236, 0, 1, vcc
	v_lshlrev_b32_e32 v237, 9, v232
	v_or_b32_e32 v220, v235, v237
	v_lshlrev_b32_e32 v237, 12, v233
	v_or_b32_e32 v220, v220, v237
	s_lshl_b32 s45, s57, 13
	s_lshl_b32 s46, s58, 15
	s_or_b32 s45, s45, s46
	s_lshl_b32 s46, s63, 20
	s_or_b32 s45, s45, s46
	v_or_b32_e32 v220, s45, v220
	v_lshlrev_b32_e32 v237, 21, v236
	v_or_b32_e32 v220, v220, v237
	v_lshlrev_b32_e32 v237, 22, v230
	v_or_b32_e32 v220, v220, v237
	v_lshl_add_u32 v237, v235, 3, v232
	v_lshlrev_b32_e32 v221, 14, v237
	v_lshlrev_b32_e32 v238, 8, v233
	v_lshl_add_u32 v224, v237, 10, v238
	v_lshlrev_b32_e32 v238, 8, v232
	v_lshl_add_u32 v222, v235, 17, v238
	s_mov_b32 s45, 0xc0000
	v_mul_lo_u32 v237, v235, s45
	s_lshl_b32 s46, s57, 6
	s_sub_u32 s46, s46, 0x5000
	v_add_u32_e32 v238, s46, v238
	v_add_u32_e32 v223, v237, v238
	s_mov_b32 s45, 0x60000
	v_mul_lo_u32 v237, v235, s45
	v_lshlrev_b32_e32 v238, 10, v233
	v_lshl_add_u32 v238, v232, 7, v238
	s_lshl_b32 s46, s57, 5
	v_add_u32_e32 v238, s46, v238
	v_add_u32_e32 v227, v237, v238
	v_lshlrev_b32_e32 v228, 6, v235
	v_mov_b32_e32 v225, s65
	v_mov_b32_e32 v226, s66
	s_mov_b32 s99, 0
	s_nop 1
	v_readlane_b32 s41, v220, 0
	v_readlane_b32 s42, v220, 1
	v_readlane_b32 s43, v220, 2
.Lp4n_top_A:
	s_mul_i32 s9, s52, 0x4400
	ds_read_b128 v[102:105], v193 offset:31232
	ds_read_b128 v[106:109], v192 offset:48640
	v_add_u32_e32 v159, s9, v190
	ds_read_b128 v[110:113], v192 offset:48704
	ds_read_b128 v[114:117], v193 offset:31296
	ds_read_b128 v[198:201], v159
	ds_read_b128 v[202:205], v159 offset:64
	s_waitcnt lgkmcnt(0)
	v_mfma_f32_16x16x32_bf16 v[102:105], v[102:105], v[106:109], 0
	s_mul_i32 s9, s52, 0x500
	s_add_i32 s87, s9, 0
	s_add_i32 s87, s87, 0x1d400
	s_waitcnt lgkmcnt(1)
	v_mfma_f32_16x16x32_bf16 v[106:109], v[198:201], v[106:109], 0
	s_cmp_lt_u32 s99, 63
	s_cselect_b64 s[10:11], -1, 0
	v_mfma_f32_16x16x32_bf16 v[102:105], v[114:117], v[110:113], v[102:105]
	ds_read_b128 v[114:117], v193 offset:31360
	ds_read_b128 v[198:201], v192 offset:48768
	s_waitcnt lgkmcnt(2)
	v_mfma_f32_16x16x32_bf16 v[106:109], v[202:205], v[110:113], v[106:109]
	ds_read_b128 v[110:113], v193 offset:31424
	ds_read_b128 v[202:205], v192 offset:48832
	s_waitcnt lgkmcnt(2)
	v_mfma_f32_16x16x32_bf16 v[102:105], v[114:117], v[198:201], v[102:105]
	ds_read_b128 v[114:117], v159 offset:128
	ds_read_b128 v[206:209], v159 offset:192
	v_lshl_add_u32 v159, v189, 2, s87
	s_waitcnt lgkmcnt(2)
	v_mfma_f32_16x16x32_bf16 v[102:105], v[110:113], v[202:205], v[102:105]
	ds_read_b128 v[110:113], v159 offset:512
	s_waitcnt lgkmcnt(2)
	v_mfma_f32_16x16x32_bf16 v[106:109], v[114:117], v[198:201], v[106:109]
	s_nop 4
	v_sub_f32_e32 v105, v101, v105
	v_sub_f32_e32 v104, v100, v104
	v_sub_f32_e32 v103, v99, v103
	v_sub_f32_e32 v102, v98, v102
	v_cvt_pk_bf16_f32 v114, v102, v103
	s_waitcnt lgkmcnt(0)
	v_pk_mul_f32 v[102:103], v[102:103], v[110:111]
	v_cvt_pk_bf16_f32 v115, v104, v105
	v_pk_mul_f32 v[104:105], v[104:105], v[112:113]
	v_cvt_pk_bf16_f32 v102, v102, v103
	v_cvt_pk_bf16_f32 v103, v104, v105
	ds_write2st64_b64 v194, v[114:115], v[102:103] offset0:112 offset1:121
	ds_read_b128 v[110:113], v159
	v_mfma_f32_16x16x32_bf16 v[114:117], v[206:209], v[202:205], v[106:109]
	s_cbranch_scc0 .Lp4n_mid_A
	s_xor_b32 s14, s52, 1
	s_bfe_u32 s45, s42, 0x1000c
	s_cmp_eq_u32 s45, 0
	s_mul_i32 s8, s14, 0x4400
	s_cselect_b64 vcc, -1, 0
	v_add_u32_e32 v102, s8, v169
	v_cndmask_b32_e32 v106, v162, v161, vcc
	v_cndmask_b32_e32 v107, v164, v163, vcc
	v_cndmask_b32_e32 v108, v166, v165, vcc
	v_cndmask_b32_e32 v109, v168, v167, vcc
	s_mul_i32 s9, s14, 0x2400
	s_waitcnt vmcnt(11)
	ds_write_b128 v102, v[34:37]
	s_waitcnt vmcnt(10)
	ds_write_b128 v102, v[38:41] offset:8704
	ds_write_b128 v170, v[26:29]
	ds_write_b128 v170, v[30:33] offset:9216
	s_waitcnt vmcnt(9)
	v_and_b32_e32 v102, v42, v106
	v_and_b32_e32 v103, v43, v107
	v_and_b32_e32 v104, v44, v108
	v_and_b32_e32 v105, v45, v109
	ds_write_b128 v171, v[102:105] offset:17408
	s_waitcnt vmcnt(8)
	v_and_b32_e32 v102, v46, v106
	v_and_b32_e32 v103, v47, v107
	v_and_b32_e32 v104, v48, v108
	v_and_b32_e32 v105, v49, v109
	v_add_u32_e32 v106, s9, v172
	s_bfe_u32 s45, s42, 0x60016
	s_cmp_lg_u32 s45, 0
	ds_write_b128 v106, v[102:105]
	s_cbranch_scc1 .Lp4n_cwkeep_A
	s_waitcnt vmcnt(4)
	v_mov_b64_e32 v[84:85], v[24:25]
	v_mov_b64_e32 v[88:89], v[20:21]
	v_mov_b64_e32 v[92:93], v[16:17]
	v_mov_b64_e32 v[96:97], v[12:13]
	v_mov_b64_e32 v[82:83], v[22:23]
	v_mov_b64_e32 v[86:87], v[18:19]
	v_mov_b64_e32 v[90:91], v[14:15]
	v_mov_b64_e32 v[94:95], v[10:11]

.Lp4n_w0done_A:
	s_or_b64 exec, exec, s[8:9]
	s_bfe_u32 s45, s42, 0x10015
	s_cmp_lg_u32 s45, 0
	s_cbranch_scc0 .Lp4n_nocwn_A
	s_cmp_lt_u32 s99, 62
	s_cbranch_scc0 .Lp4n_nocwn_A
	s_bfe_u32 s14, s43, 0x30009
	s_lshl_b32 s14, s14, 7
	s_bfe_u32 s8, s43, 0x2000d
	s_lshl_b32 s8, s8, 5
	s_lshl_b64 s[20:21], s[14:15], 2
	s_mov_b32 s9, s15
	s_add_u32 s14, s33, s20
	s_addc_u32 s23, s34, s21
	s_lshl_b64 s[8:9], s[8:9], 2
	s_add_u32 s22, s14, s8
	s_addc_u32 s23, s23, s9
	s_add_u32 s14, s35, s20
	s_addc_u32 s93, s36, s21
	s_add_u32 s92, s14, s8
	s_addc_u32 s93, s93, s9
	v_lshlrev_b32_e32 v22, 2, v178
	s_add_u32 s14, s37, s20
	global_load_dwordx4 v[10:13], v22, s[22:23]
	global_load_dwordx4 v[14:17], v22, s[92:93]
	s_addc_u32 s23, s38, s21
	s_add_u32 s22, s14, s8
	s_addc_u32 s23, s23, s9
	s_add_u32 s14, s39, s20
	s_addc_u32 s20, s40, s21
	s_add_u32 s8, s14, s8
	s_addc_u32 s9, s20, s9
	global_load_dwordx4 v[18:21], v22, s[22:23]
	s_nop 0
	global_load_dwordx4 v[22:25], v22, s[8:9]
.Lp4n_nocwn_A:
	s_cmp_lt_u32 s99, 61
	s_cbranch_scc0 .Lp4n_mid_A
	s_add_u32 s46, s99, 3
	s_nop 3
	v_readlane_b32 s8, v221, s46
	v_readlane_b32 s88, v222, s46
	v_readlane_b32 s20, v223, s46
	v_readlane_b32 s47, v224, s46
	v_readlane_b32 s76, v225, s46
	v_readlane_b32 s77, v226, s46
	v_readlane_b32 s22, v228, s46
	v_readlane_b32 s44, v220, s46
	s_mov_b32 s9, 0
	s_add_u32 s88, s72, s88
	s_addc_u32 s89, s73, 0
	s_nop 1
	v_lshl_add_u64 v[26:27], v[152:153], 0, s[8:9]
	v_add_co_u32_e32 v30, vcc, s49, v26
	v_lshl_add_u64 v[34:35], s[88:89], 0, v[118:119]
	s_nop 0
	v_addc_co_u32_e32 v31, vcc, 0, v27, vcc
	v_add_co_u32_e32 v38, vcc, 0x10000, v34
	v_lshl_add_u64 v[42:43], v[154:155], 0, s[8:9]
	s_nop 0
	v_addc_co_u32_e32 v39, vcc, 0, v35, vcc
	v_add_co_u32_e32 v46, vcc, 0x2000, v42
	global_load_dwordx4 v[26:29], v[26:27], off
	s_nop 0
	global_load_dwordx4 v[30:33], v[30:31], off
	v_addc_co_u32_e32 v47, vcc, 0, v43, vcc
	global_load_dwordx4 v[34:37], v[34:35], off
	s_nop 0
	global_load_dwordx4 v[38:41], v[38:39], off
	s_nop 0
	global_load_dwordx4 v[42:45], v[42:43], off
	s_nop 0
	global_load_dwordx4 v[46:49], v[46:47], off
	s_ashr_i32 s89, s20, 31
	s_add_u32 s88, s0, s20
	s_addc_u32 s89, s1, s89
	v_add_u32_e32 v102, s22, v160
	v_cmp_le_i32_e32 vcc, s76, v102
	v_cmp_gt_i32_e64 s[8:9], s77, v102
	v_mov_b32_e32 v130, v158
	v_mov_b32_e32 v131, v158
	s_and_b64 s[90:91], vcc, s[8:9]
	v_lshl_add_u64 v[102:103], s[88:89], 0, v[120:121]
	v_mov_b64_e32 v[128:129], v[130:131]
	s_and_saveexec_b64 s[8:9], s[90:91]
	s_cbranch_execz .Lp4n_v0_A
	global_load_dwordx2 v[128:129], v[102:103], off

.Lp4n_v3_A:
	s_or_b64 exec, exec, s[8:9]
	s_add_u32 s8, s30, s47
	s_addc_u32 s9, s31, 0
	v_lshl_add_u64 v[102:103], s[8:9], 0, v[122:123]
	global_load_dword v175, v[102:103], off offset:512
	v_mov_b32_e32 v177, 0
	v_mov_b32_e32 v176, 0
	s_and_saveexec_b64 s[20:21], s[4:5]
	s_cbranch_execz .Lp4n_gdone_A
	v_lshl_add_u64 v[102:103], s[8:9], 0, v[124:125]
	global_load_dword v176, v[102:103], off
	global_load_dword v177, v[102:103], off offset:512

.Lp4n_mid_A:
	s_waitcnt lgkmcnt(0)
	s_barrier
	v_mov_b32_e32 v102, s87
	ds_read_b32 v198, v102 offset:768
	ds_read_b128 v[102:105], v196 offset:61952
	ds_read_b128 v[106:109], v196 offset:64256
	s_mul_i32 s8, s52, 0x2400
	v_add_u32_e32 v159, s8, v191
	s_waitcnt lgkmcnt(2)
	v_pk_mul_f32 v[4:5], v[4:5], v[198:199] op_sel_hi:[1,0]
	v_pk_mul_f32 v[2:3], v[2:3], v[198:199] op_sel_hi:[1,0]
	v_pk_mul_f32 v[8:9], v[8:9], v[198:199] op_sel_hi:[1,0]
	v_pk_mul_f32 v[6:7], v[6:7], v[198:199] op_sel_hi:[1,0]
	s_waitcnt lgkmcnt(1)
	v_mfma_f32_16x16x32_bf16 v[2:5], v[74:77], v[102:105], v[2:5]
	ds_read_b128 v[102:105], v196 offset:62016
	s_waitcnt lgkmcnt(1)
	v_mfma_f32_16x16x32_bf16 v[6:9], v[74:77], v[106:109], v[6:9]
	v_readlane_b32 s8, v227, s99
	s_mov_b32 s9, 0
	s_waitcnt lgkmcnt(0)
	v_mfma_f32_16x16x32_bf16 v[102:105], v[78:81], v[102:105], v[2:5]
	s_nop 2
	ds_read_b128 v[2:5], v196 offset:64320
	ds_read_b128 v[198:201], v159
	ds_read_b128 v[202:205], v187 offset:57344
	s_waitcnt lgkmcnt(2)
	v_mfma_f32_16x16x32_bf16 v[106:109], v[78:81], v[2:5], v[6:9]
	v_mul_f32_e64 v4, v116, v112
	v_mul_f32_e64 v5, v117, v113
	v_pk_mul_f32 v[2:3], v[114:115], v[110:111]
	ds_read_b128 v[110:113], v159 offset:64
	ds_read_b128 v[6:9], v187 offset:57408
	s_waitcnt lgkmcnt(2)
	v_mfma_f32_16x16x32_bf16 v[2:5], v[198:201], v[202:205], v[2:5]
	s_bfe_u32 s45, s41, 0x10015
	s_cmp_eq_u32 s45, 0
	s_waitcnt lgkmcnt(0)
	v_mfma_f32_16x16x32_bf16 v[2:5], v[110:113], v[6:9], v[2:5]
	v_lshl_add_u64 v[6:7], s[8:9], 1, v[156:157]
	s_movk_i32 s8, 0x6000
	s_nop 5
	v_cvt_pk_bf16_f32 v2, v2, s0
	global_store_short v[6:7], v2, off
	v_add_co_u32_e32 v2, vcc, s50, v6
	v_cvt_pk_bf16_f32 v8, v3, s0
	s_nop 0
	v_addc_co_u32_e32 v3, vcc, 0, v7, vcc
	global_store_short v[2:3], v8, off
	v_add_co_u32_e32 v2, vcc, s8, v6
	v_cvt_pk_bf16_f32 v4, v4, s0
	s_nop 0
	v_addc_co_u32_e32 v3, vcc, 0, v7, vcc
	global_store_short v[2:3], v4, off
	v_add_co_u32_e32 v2, vcc, 0x9000, v6
	v_cvt_pk_bf16_f32 v4, v5, s0
	s_nop 0
	v_addc_co_u32_e32 v3, vcc, 0, v7, vcc
	global_store_short v[2:3], v4, off
	s_cbranch_scc1 .Lp4n_sjoin_A
	s_bfe_u32 s45, s41, 0x10014
	s_cmp_lg_u32 s45, 0
	s_cbranch_scc1 .Lp4n_nosst_A
	s_bfe_u32 s8, s41, 0x5000f
	s_lshl_b32 s8, s8, 4
	s_bfe_u32 s9, s41, 0x1000c
	s_lshl_b32 s9, s9, 3
	s_bfe_u32 s14, s41, 0x30009
	s_add_i32 s8, s14, s8
	s_bfe_u32 s14, s41, 0x2000d
	s_lshl_b32 s14, s14, 5
	s_add_i32 s8, s8, s9
	s_ashr_i32 s9, s8, 31
	s_lshl_b64 s[8:9], s[8:9], 16
	s_add_u32 s20, s72, s8
	s_addc_u32 s21, s73, s9
	s_lshl_b64 s[8:9], s[14:15], 2
	s_add_u32 s8, s20, s8
	s_addc_u32 s9, s21, s9
	v_lshl_add_u64 v[2:3], s[8:9], 0, v[126:127]
	v_lshl_add_u64 v[2:3], v[2:3], 0, s[18:19]
	v_lshl_add_u64 v[4:5], v[2:3], 0, v[144:145]
	v_lshl_add_u64 v[6:7], v[2:3], 0, v[146:147]
	v_lshl_add_u64 v[8:9], v[2:3], 0, v[148:149]
	v_lshl_add_u64 v[2:3], v[2:3], 0, v[150:151]
	global_store_dword v[4:5], v102, off
	global_store_dword v[6:7], v103, off
	global_store_dword v[8:9], v104, off
	global_store_dword v[2:3], v105, off
	global_store_dword v[4:5], v106, off offset:64
	global_store_dword v[6:7], v107, off offset:64
	global_store_dword v[8:9], v108, off offset:64
	global_store_dword v[2:3], v109, off offset:64
.Lp4n_nosst_A:
	s_andn2_b64 vcc, exec, s[10:11]
	s_cbranch_vccnz .Lp4n_sjoin_A
	v_mov_b32_e32 v102, 0
	v_mov_b32_e32 v103, 0
	v_mov_b32_e32 v104, 0
	v_mov_b32_e32 v105, 0
	v_mov_b32_e32 v106, 0
	v_mov_b32_e32 v107, 0
	v_mov_b32_e32 v108, 0
	v_mov_b32_e32 v109, 0

.Lp4n_end_A:
	s_waitcnt lgkmcnt(0)
	s_barrier
	s_cmp_lt_u32 s99, 63
	s_cbranch_scc0 .Lp4n_exit
	s_add_u32 s99, s99, 1
	s_xor_b32 s52, s52, 1
	s_mov_b32 s41, s42
	s_mov_b32 s42, s43
	s_mov_b32 s43, s44
.Lp4n_top_B:
	s_mul_i32 s9, s52, 0x4400
	ds_read_b128 v[2:5], v193 offset:31232
	ds_read_b128 v[6:9], v192 offset:48640
	v_add_u32_e32 v159, s9, v190
	ds_read_b128 v[110:113], v192 offset:48704
	ds_read_b128 v[114:117], v193 offset:31296
	ds_read_b128 v[198:201], v159
	ds_read_b128 v[202:205], v159 offset:64
	s_waitcnt lgkmcnt(0)
	v_mfma_f32_16x16x32_bf16 v[2:5], v[2:5], v[6:9], 0
	s_mul_i32 s9, s52, 0x500
	s_add_i32 s87, s9, 0
	s_add_i32 s87, s87, 0x1d400
	s_waitcnt lgkmcnt(1)
	v_mfma_f32_16x16x32_bf16 v[6:9], v[198:201], v[6:9], 0
	s_cmp_lt_u32 s99, 63
	s_cselect_b64 s[10:11], -1, 0
	v_mfma_f32_16x16x32_bf16 v[2:5], v[114:117], v[110:113], v[2:5]
	ds_read_b128 v[114:117], v193 offset:31360
	ds_read_b128 v[198:201], v192 offset:48768
	s_waitcnt lgkmcnt(2)
	v_mfma_f32_16x16x32_bf16 v[6:9], v[202:205], v[110:113], v[6:9]
	ds_read_b128 v[110:113], v193 offset:31424
	ds_read_b128 v[202:205], v192 offset:48832
	s_waitcnt lgkmcnt(2)
	v_mfma_f32_16x16x32_bf16 v[2:5], v[114:117], v[198:201], v[2:5]
	ds_read_b128 v[114:117], v159 offset:128
	ds_read_b128 v[206:209], v159 offset:192
	v_lshl_add_u32 v159, v189, 2, s87
	s_waitcnt lgkmcnt(2)
	v_mfma_f32_16x16x32_bf16 v[2:5], v[110:113], v[202:205], v[2:5]
	ds_read_b128 v[110:113], v159 offset:512
	s_waitcnt lgkmcnt(2)
	v_mfma_f32_16x16x32_bf16 v[6:9], v[114:117], v[198:201], v[6:9]
	s_nop 4
	v_sub_f32_e32 v5, v101, v5
	v_sub_f32_e32 v4, v100, v4
	v_sub_f32_e32 v3, v99, v3
	v_sub_f32_e32 v2, v98, v2
	v_cvt_pk_bf16_f32 v114, v2, v3
	s_waitcnt lgkmcnt(0)
	v_pk_mul_f32 v[2:3], v[2:3], v[110:111]
	v_cvt_pk_bf16_f32 v115, v4, v5
	v_pk_mul_f32 v[4:5], v[4:5], v[112:113]
	v_cvt_pk_bf16_f32 v2, v2, v3
	v_cvt_pk_bf16_f32 v3, v4, v5
	ds_write2st64_b64 v194, v[114:115], v[2:3] offset0:112 offset1:121
	ds_read_b128 v[110:113], v159
	v_mfma_f32_16x16x32_bf16 v[114:117], v[206:209], v[202:205], v[6:9]
	s_cbranch_scc0 .Lp4n_mid_B
	s_xor_b32 s14, s52, 1
	s_bfe_u32 s45, s42, 0x1000c
	s_cmp_eq_u32 s45, 0
	s_mul_i32 s8, s14, 0x4400
	s_cselect_b64 vcc, -1, 0
	v_add_u32_e32 v2, s8, v169
	v_cndmask_b32_e32 v6, v162, v161, vcc
	v_cndmask_b32_e32 v7, v164, v163, vcc
	v_cndmask_b32_e32 v8, v166, v165, vcc
	v_cndmask_b32_e32 v9, v168, v167, vcc
	s_mul_i32 s9, s14, 0x2400
	s_waitcnt vmcnt(11)
	ds_write_b128 v2, v[58:61]
	s_waitcnt vmcnt(10)
	ds_write_b128 v2, v[62:65] offset:8704
	ds_write_b128 v170, v[50:53]
	ds_write_b128 v170, v[54:57] offset:9216
	s_waitcnt vmcnt(9)
	v_and_b32_e32 v2, v66, v6
	v_and_b32_e32 v3, v67, v7
	v_and_b32_e32 v4, v68, v8
	v_and_b32_e32 v5, v69, v9
	ds_write_b128 v171, v[2:5] offset:17408
	s_waitcnt vmcnt(8)
	v_and_b32_e32 v2, v70, v6
	v_and_b32_e32 v3, v71, v7
	v_and_b32_e32 v4, v72, v8
	v_and_b32_e32 v5, v73, v9
	v_add_u32_e32 v6, s9, v172
	s_bfe_u32 s45, s42, 0x60016
	s_cmp_lg_u32 s45, 0
	ds_write_b128 v6, v[2:5]
	s_cbranch_scc1 .Lp4n_cwkeep_B
	s_waitcnt vmcnt(4)
	v_mov_b64_e32 v[84:85], v[24:25]
	v_mov_b64_e32 v[88:89], v[20:21]
	v_mov_b64_e32 v[92:93], v[16:17]
	v_mov_b64_e32 v[96:97], v[12:13]
	v_mov_b64_e32 v[82:83], v[22:23]
	v_mov_b64_e32 v[86:87], v[18:19]
	v_mov_b64_e32 v[90:91], v[14:15]
	v_mov_b64_e32 v[94:95], v[10:11]
.Lp4n_cwkeep_B:
	v_lshlrev_b32_e32 v2, 16, v134
	v_fma_f32 v2, v94, v2, 0
	v_and_b32_e32 v3, 0xffff0000, v134
	v_lshlrev_b32_e32 v6, 16, v138
	v_fma_f32 v3, v95, v3, 0
	v_lshlrev_b32_e32 v4, 16, v135
	v_fmac_f32_e32 v2, v90, v6
	v_and_b32_e32 v6, 0xffff0000, v138
	v_fma_f32 v4, v96, v4, 0
	v_and_b32_e32 v5, 0xffff0000, v135
	v_fmac_f32_e32 v3, v91, v6
	v_lshlrev_b32_e32 v6, 16, v139
	v_fma_f32 v5, v97, v5, 0
	v_fmac_f32_e32 v4, v92, v6
	v_and_b32_e32 v6, 0xffff0000, v139
	v_fmac_f32_e32 v5, v93, v6
	v_lshlrev_b32_e32 v6, 16, v140
	v_fmac_f32_e32 v2, v86, v6
	v_and_b32_e32 v6, 0xffff0000, v140
	v_fmac_f32_e32 v3, v87, v6
	v_lshlrev_b32_e32 v6, 16, v141
	v_fmac_f32_e32 v4, v88, v6
	v_and_b32_e32 v6, 0xffff0000, v141
	v_fmac_f32_e32 v5, v89, v6
	v_lshlrev_b32_e32 v6, 16, v142
	v_fmac_f32_e32 v2, v82, v6
	v_mul_f32_e32 v6, 0xbfb8aa3b, v2
	v_exp_f32_e32 v6, v6
	v_and_b32_e32 v7, 0xffff0000, v142
	v_fmac_f32_e32 v3, v83, v7
	v_lshlrev_b32_e32 v7, 16, v143
	v_add_f32_e32 v6, 1.0, v6
	v_rcp_f32_e32 v6, v6
	v_fmac_f32_e32 v4, v84, v7
	v_mul_f32_e32 v8, 0xbfb8aa3b, v4
	v_exp_f32_e32 v8, v8
	v_mul_f32_e32 v2, v2, v6
	v_mul_f32_e32 v6, 0xbfb8aa3b, v3
	v_exp_f32_e32 v6, v6
	v_and_b32_e32 v7, 0xffff0000, v143
	s_waitcnt vmcnt(7)
	v_mul_f32_e32 v2, v181, v2
	v_fmac_f32_e32 v5, v85, v7
	v_add_f32_e32 v6, 1.0, v6
	v_rcp_f32_e32 v6, v6
	v_cvt_pk_bf16_f32 v2, v2, s0
	v_add_u32_e32 v7, v173, v182
	ds_write_b16 v7, v2 offset:26624
	v_mul_f32_e32 v2, v3, v6
	v_add_f32_e32 v3, 1.0, v8
	v_mul_f32_e32 v6, 0xbfb8aa3b, v5
	v_rcp_f32_e32 v3, v3
	v_exp_f32_e32 v6, v6
	v_mul_f32_e32 v2, v181, v2
	v_cvt_pk_bf16_f32 v2, v2, s0
	ds_write_b16 v7, v2 offset:26768
	v_mul_f32_e32 v2, v4, v3
	v_add_f32_e32 v3, 1.0, v6
	v_rcp_f32_e32 v3, v3
	v_mul_f32_e32 v2, v181, v2
	v_cvt_pk_bf16_f32 v2, v2, s0
	ds_write_b16 v7, v2 offset:26912
	v_mul_f32_e32 v2, v5, v3
	v_mul_f32_e32 v2, v181, v2
	v_cvt_pk_bf16_f32 v2, v2, s0
	ds_write_b16 v7, v2 offset:27056
	s_and_saveexec_b64 s[8:9], s[4:5]
	s_cbranch_execz .Lp4n_w0done_B
	s_mulk_i32 s14, 0x500
	s_add_i32 s14, s14, 0
	s_add_i32 s14, s14, 0x1d400
	s_and_b64 s[20:21], vcc, exec
	s_cselect_b32 s20, 63, 0
	v_and_or_b32 v2, v195, 64, s20
	v_lshlrev_b32_e32 v2, 2, v2
	ds_bpermute_b32 v2, v2, v184
	v_mul_f32_e32 v3, 0x3fb8aa3b, v184
	v_exp_f32_e32 v3, v3
	v_lshl_add_u32 v5, v0, 2, s14
	s_waitcnt lgkmcnt(0)
	v_sub_f32_e32 v4, v2, v184
	v_mul_f32_e32 v4, 0x3fb8aa3b, v4
	v_exp_f32_e32 v4, v4
	v_mul_f32_e32 v6, v185, v3
	ds_write2st64_b32 v5, v3, v6 offset1:1
	ds_write_b32 v5, v4 offset:512
	s_and_b64 exec, exec, s[6:7]
	s_cbranch_execz .Lp4n_w0done_B
	v_mul_f32_e32 v2, 0x3fb8aa3b, v2
	v_exp_f32_e32 v2, v2
	v_mov_b32_e32 v3, s14
	ds_write_b32 v3, v2 offset:768

.Lp4n_nocwn_B:
	s_cmp_lt_u32 s99, 61
	s_cbranch_scc0 .Lp4n_mid_B
	s_add_u32 s46, s99, 3
	s_nop 3
	v_readlane_b32 s8, v221, s46
	v_readlane_b32 s88, v222, s46
	v_readlane_b32 s20, v223, s46
	v_readlane_b32 s47, v224, s46
	v_readlane_b32 s76, v225, s46
	v_readlane_b32 s77, v226, s46
	v_readlane_b32 s22, v228, s46
	v_readlane_b32 s44, v220, s46
	s_mov_b32 s9, 0
	s_add_u32 s88, s72, s88
	s_addc_u32 s89, s73, 0
	s_nop 1
	v_lshl_add_u64 v[50:51], v[152:153], 0, s[8:9]
	v_add_co_u32_e32 v54, vcc, s49, v50
	v_lshl_add_u64 v[58:59], s[88:89], 0, v[118:119]
	s_nop 0
	v_addc_co_u32_e32 v55, vcc, 0, v51, vcc
	v_add_co_u32_e32 v62, vcc, 0x10000, v58
	v_lshl_add_u64 v[66:67], v[154:155], 0, s[8:9]
	s_nop 0
	v_addc_co_u32_e32 v63, vcc, 0, v59, vcc
	v_add_co_u32_e32 v70, vcc, 0x2000, v66
	global_load_dwordx4 v[50:53], v[50:51], off
	s_nop 0
	global_load_dwordx4 v[54:57], v[54:55], off
	v_addc_co_u32_e32 v71, vcc, 0, v67, vcc
	global_load_dwordx4 v[58:61], v[58:59], off
	s_nop 0
	global_load_dwordx4 v[62:65], v[62:63], off
	s_nop 0
	global_load_dwordx4 v[66:69], v[66:67], off
	s_nop 0
	global_load_dwordx4 v[70:73], v[70:71], off
	s_ashr_i32 s89, s20, 31
	s_add_u32 s88, s0, s20
	s_addc_u32 s89, s1, s89
	v_add_u32_e32 v2, s22, v160
	v_cmp_le_i32_e32 vcc, s76, v2
	v_cmp_gt_i32_e64 s[8:9], s77, v2
	v_mov_b32_e32 v138, v158
	v_mov_b32_e32 v139, v158
	s_and_b64 s[90:91], vcc, s[8:9]
	v_lshl_add_u64 v[2:3], s[88:89], 0, v[120:121]
	v_mov_b64_e32 v[134:135], v[138:139]
	s_and_saveexec_b64 s[8:9], s[90:91]
	s_cbranch_execz .Lp4n_v0_B
	global_load_dwordx2 v[134:135], v[2:3], off
.Lp4n_v0_B:
	s_or_b64 exec, exec, s[8:9]
	v_add3_u32 v4, v160, s22, 1
	v_cmp_le_i32_e32 vcc, s76, v4
	v_cmp_gt_i32_e64 s[8:9], s77, v4
	s_and_b64 s[88:89], vcc, s[8:9]
	s_and_saveexec_b64 s[8:9], s[88:89]
	s_cbranch_execz .Lp4n_v1_B
	v_add_co_u32_e32 v4, vcc, 0x3000, v2
	s_nop 1
	v_addc_co_u32_e32 v5, vcc, 0, v3, vcc
	global_load_dwordx2 v[138:139], v[4:5], off
.Lp4n_v1_B:
	s_or_b64 exec, exec, s[8:9]
	v_add3_u32 v4, v160, s22, 2
	v_cmp_le_i32_e32 vcc, s76, v4
	v_cmp_gt_i32_e64 s[8:9], s77, v4
	v_mov_b32_e32 v159, v158
	s_and_b64 s[88:89], vcc, s[8:9]
	v_mov_b64_e32 v[140:141], v[158:159]
	s_and_saveexec_b64 s[8:9], s[88:89]
	s_cbranch_execz .Lp4n_v2_B
	v_add_co_u32_e32 v4, vcc, 0x6000, v2
	s_nop 1
	v_addc_co_u32_e32 v5, vcc, 0, v3, vcc
	global_load_dwordx2 v[140:141], v[4:5], off
.Lp4n_v2_B:
	s_or_b64 exec, exec, s[8:9]
	v_add3_u32 v4, v160, s22, 3
	v_cmp_le_i32_e32 vcc, s76, v4
	v_cmp_gt_i32_e64 s[8:9], s77, v4
	s_and_b64 s[22:23], vcc, s[8:9]
	v_mov_b64_e32 v[142:143], v[158:159]
	s_and_saveexec_b64 s[8:9], s[22:23]
	s_cbranch_execz .Lp4n_v3_B
	v_add_co_u32_e32 v2, vcc, 0x9000, v2
	s_nop 1
	v_addc_co_u32_e32 v3, vcc, 0, v3, vcc
	global_load_dwordx2 v[142:143], v[2:3], off
.Lp4n_v3_B:
	s_or_b64 exec, exec, s[8:9]
	s_add_u32 s8, s30, s47
	s_addc_u32 s9, s31, 0
	v_lshl_add_u64 v[2:3], s[8:9], 0, v[122:123]
	global_load_dword v181, v[2:3], off offset:512
	v_mov_b32_e32 v185, 0
	v_mov_b32_e32 v184, 0
	s_and_saveexec_b64 s[20:21], s[4:5]
	s_cbranch_execz .Lp4n_gdone_B
	v_lshl_add_u64 v[2:3], s[8:9], 0, v[124:125]
	global_load_dword v184, v[2:3], off
	global_load_dword v185, v[2:3], off offset:512

.Lp4n_mid_B:
	s_waitcnt lgkmcnt(0)
	s_barrier
	v_mov_b32_e32 v2, s87
	ds_read_b32 v198, v2 offset:768
	ds_read_b128 v[2:5], v196 offset:61952
	ds_read_b128 v[6:9], v196 offset:64256
	s_mul_i32 s8, s52, 0x2400
	v_add_u32_e32 v159, s8, v191
	s_waitcnt lgkmcnt(2)
	v_pk_mul_f32 v[104:105], v[104:105], v[198:199] op_sel_hi:[1,0]
	v_pk_mul_f32 v[102:103], v[102:103], v[198:199] op_sel_hi:[1,0]
	v_pk_mul_f32 v[108:109], v[108:109], v[198:199] op_sel_hi:[1,0]
	v_pk_mul_f32 v[106:107], v[106:107], v[198:199] op_sel_hi:[1,0]
	s_waitcnt lgkmcnt(1)
	v_mfma_f32_16x16x32_bf16 v[102:105], v[74:77], v[2:5], v[102:105]
	ds_read_b128 v[2:5], v196 offset:62016
	s_waitcnt lgkmcnt(1)
	v_mfma_f32_16x16x32_bf16 v[106:109], v[74:77], v[6:9], v[106:109]
	v_readlane_b32 s8, v227, s99
	s_mov_b32 s9, 0
	s_waitcnt lgkmcnt(0)
	v_mfma_f32_16x16x32_bf16 v[2:5], v[78:81], v[2:5], v[102:105]
	s_nop 2
	ds_read_b128 v[102:105], v196 offset:64320
	ds_read_b128 v[198:201], v159
	ds_read_b128 v[202:205], v187 offset:57344
	s_waitcnt lgkmcnt(2)
	v_mfma_f32_16x16x32_bf16 v[6:9], v[78:81], v[102:105], v[106:109]
	v_mul_f32_e64 v104, v116, v112
	v_mul_f32_e64 v105, v117, v113
	v_pk_mul_f32 v[102:103], v[114:115], v[110:111]
	ds_read_b128 v[110:113], v159 offset:64
	ds_read_b128 v[106:109], v187 offset:57408
	s_waitcnt lgkmcnt(2)
	v_mfma_f32_16x16x32_bf16 v[102:105], v[198:201], v[202:205], v[102:105]
	s_bfe_u32 s45, s41, 0x10015
	s_cmp_eq_u32 s45, 0
	s_waitcnt lgkmcnt(0)
	v_mfma_f32_16x16x32_bf16 v[102:105], v[110:113], v[106:109], v[102:105]
	v_lshl_add_u64 v[106:107], s[8:9], 1, v[156:157]
	s_movk_i32 s8, 0x6000
	s_nop 5
	v_cvt_pk_bf16_f32 v102, v102, s0
	global_store_short v[106:107], v102, off
	v_add_co_u32_e32 v102, vcc, s50, v106
	v_cvt_pk_bf16_f32 v108, v103, s0
	s_nop 0
	v_addc_co_u32_e32 v103, vcc, 0, v107, vcc
	global_store_short v[102:103], v108, off
	v_add_co_u32_e32 v102, vcc, s8, v106
	v_cvt_pk_bf16_f32 v104, v104, s0
	s_nop 0
	v_addc_co_u32_e32 v103, vcc, 0, v107, vcc
	global_store_short v[102:103], v104, off
	v_add_co_u32_e32 v102, vcc, 0x9000, v106
	v_cvt_pk_bf16_f32 v104, v105, s0
	s_nop 0
	v_addc_co_u32_e32 v103, vcc, 0, v107, vcc
	global_store_short v[102:103], v104, off
	s_cbranch_scc1 .Lp4n_sjoin_B
	s_bfe_u32 s45, s41, 0x10014
	s_cmp_lg_u32 s45, 0
	s_cbranch_scc1 .Lp4n_nosst_B
	s_bfe_u32 s8, s41, 0x5000f
	s_lshl_b32 s8, s8, 4
	s_bfe_u32 s9, s41, 0x1000c
	s_lshl_b32 s9, s9, 3
	s_bfe_u32 s14, s41, 0x30009
	s_add_i32 s8, s14, s8
	s_bfe_u32 s14, s41, 0x2000d
	s_lshl_b32 s14, s14, 5
	s_add_i32 s8, s8, s9
	s_ashr_i32 s9, s8, 31
	s_lshl_b64 s[8:9], s[8:9], 16
	s_add_u32 s20, s72, s8
	s_addc_u32 s21, s73, s9
	s_lshl_b64 s[8:9], s[14:15], 2
	s_add_u32 s8, s20, s8
	s_addc_u32 s9, s21, s9
	v_lshl_add_u64 v[102:103], s[8:9], 0, v[126:127]
	v_lshl_add_u64 v[102:103], v[102:103], 0, s[18:19]
	v_lshl_add_u64 v[104:105], v[102:103], 0, v[144:145]
	v_lshl_add_u64 v[106:107], v[102:103], 0, v[146:147]
	v_lshl_add_u64 v[108:109], v[102:103], 0, v[148:149]
	v_lshl_add_u64 v[102:103], v[102:103], 0, v[150:151]
	global_store_dword v[104:105], v2, off
	global_store_dword v[106:107], v3, off
	global_store_dword v[108:109], v4, off
	global_store_dword v[102:103], v5, off
	global_store_dword v[104:105], v6, off offset:64
	global_store_dword v[106:107], v7, off offset:64
	global_store_dword v[108:109], v8, off offset:64
	global_store_dword v[102:103], v9, off offset:64
.Lp4n_nosst_B:
	s_andn2_b64 vcc, exec, s[10:11]
	s_cbranch_vccnz .Lp4n_sjoin_B
	v_mov_b32_e32 v2, 0
	v_mov_b32_e32 v3, 0
	v_mov_b32_e32 v4, 0
	v_mov_b32_e32 v5, 0
	v_mov_b32_e32 v6, 0
	v_mov_b32_e32 v7, 0
	v_mov_b32_e32 v8, 0
	v_mov_b32_e32 v9, 0
.Lp4n_sjoin_B:
	s_nop 0
	v_cvt_pk_bf16_f32 v102, v2, v3
	v_cvt_pk_bf16_f32 v103, v4, v5
	v_cndmask_b32_e64 v104, 0, 1, s[10:11]
	ds_write_b64 v183, v[102:103] offset:48640
	v_cvt_pk_bf16_f32 v102, v6, v7
	v_cvt_pk_bf16_f32 v103, v8, v9
	v_cmp_ne_u32_e64 s[8:9], 1, v104
	s_andn2_b64 vcc, exec, s[10:11]
	ds_write_b64 v183, v[102:103] offset:52992
	s_cbranch_vccnz .Lp4n_end_B
	s_xor_b32 s10, s52, 1
	s_mulk_i32 s10, 0x500
	s_add_i32 s10, s10, 0
	ds_read_b128 v[74:77], v179
	v_add_u32_e32 v102, s10, v180
	v_add_u32_e32 v159, 0x1d500, v102
	ds_read_b128 v[102:105], v159
	ds_read_b128 v[106:109], v159 offset:16
	ds_read_b128 v[78:81], v179 offset:64
	s_waitcnt lgkmcnt(3)
	v_lshlrev_b32_e32 v98, 16, v74
	v_and_b32_e32 v99, 0xffff0000, v74
	s_waitcnt lgkmcnt(2)
	v_pk_mul_f32 v[102:103], v[102:103], v[98:99]
	v_lshlrev_b32_e32 v98, 16, v75
	v_and_b32_e32 v99, 0xffff0000, v75
	v_pk_mul_f32 v[104:105], v[104:105], v[98:99]
	v_cvt_pk_bf16_f32 v102, v102, v103
	v_cvt_pk_bf16_f32 v103, v104, v105
	v_lshlrev_b32_e32 v104, 16, v76
	v_and_b32_e32 v105, 0xffff0000, v76
	s_waitcnt lgkmcnt(1)
	v_pk_mul_f32 v[104:105], v[106:107], v[104:105]
	v_lshlrev_b32_e32 v106, 16, v77
	v_and_b32_e32 v107, 0xffff0000, v77
	v_pk_mul_f32 v[106:107], v[108:109], v[106:107]
	v_cvt_pk_bf16_f32 v104, v104, v105
	v_cvt_pk_bf16_f32 v105, v106, v107
	ds_read_b128 v[106:109], v196 offset:17408
	ds_read_b128 v[98:101], v196 offset:17472
	ds_read_b128 v[110:113], v196 offset:19712
	ds_read_b128 v[114:117], v196 offset:19776
	ds_read_b128 v[198:201], v196 offset:22016
	ds_read_b128 v[202:205], v196 offset:22080
	ds_read_b128 v[206:209], v196 offset:24320
	ds_read_b128 v[210:213], v159 offset:128
	ds_read_b128 v[214:217], v196 offset:24384
	s_waitcnt lgkmcnt(8)
	v_mfma_f32_16x16x32_bf16 v[106:109], v[102:105], v[106:109], 0
	v_lshlrev_b32_e32 v218, 16, v78
	v_and_b32_e32 v219, 0xffff0000, v78
	s_waitcnt lgkmcnt(1)
	v_pk_mul_f32 v[210:211], v[210:211], v[218:219]
	v_mfma_f32_16x16x32_bf16 v[110:113], v[102:105], v[110:113], 0
	v_lshlrev_b32_e32 v218, 16, v79
	v_and_b32_e32 v219, 0xffff0000, v79
	v_pk_mul_f32 v[212:213], v[212:213], v[218:219]
	v_mfma_f32_16x16x32_bf16 v[198:201], v[102:105], v[198:201], 0
	v_cvt_pk_bf16_f32 v210, v210, v211
	v_cvt_pk_bf16_f32 v211, v212, v213
	v_lshlrev_b32_e32 v212, 16, v80
	v_mfma_f32_16x16x32_bf16 v[102:105], v[102:105], v[206:209], 0
	ds_read_b128 v[206:209], v159 offset:144
	v_and_b32_e32 v213, 0xffff0000, v80
	s_waitcnt lgkmcnt(0)
	v_pk_mul_f32 v[206:207], v[206:207], v[212:213]
	s_nop 0
	v_cvt_pk_bf16_f32 v212, v206, v207
	v_lshlrev_b32_e32 v206, 16, v81
	v_and_b32_e32 v207, 0xffff0000, v81
	v_pk_mul_f32 v[206:207], v[208:209], v[206:207]
	s_nop 0
	v_cvt_pk_bf16_f32 v213, v206, v207
	s_nop 1
	v_mfma_f32_16x16x32_bf16 v[106:109], v[210:213], v[98:101], v[106:109]
	v_mfma_f32_16x16x32_bf16 v[98:101], v[210:213], v[114:117], v[110:113]
	s_nop 6
	v_cvt_pk_bf16_f32 v106, v106, v107
	v_cvt_pk_bf16_f32 v107, v108, v109
	ds_write_b64 v183, v[106:107] offset:31232
	v_mfma_f32_16x16x32_bf16 v[110:113], v[210:213], v[202:205], v[198:201]
	v_add_u32_e32 v108, v174, v188
	v_cvt_pk_bf16_f32 v106, v98, v99
	v_cvt_pk_bf16_f32 v107, v100, v101
	v_mfma_f32_16x16x32_bf16 v[102:105], v[210:213], v[214:217], v[102:105]
	ds_write_b64 v183, v[106:107] offset:35584
	s_nop 2
	v_cvt_pk_bf16_f32 v106, v110, v111
	v_cvt_pk_bf16_f32 v107, v112, v113
	ds_write_b64 v108, v[106:107] offset:31232
	s_nop 0
	v_cvt_pk_bf16_f32 v102, v102, v103
	v_cvt_pk_bf16_f32 v103, v104, v105
	ds_write_b64 v108, v[102:103] offset:35584
	ds_read_b128 v[102:105], v186 offset:17408
	ds_read_b128 v[106:109], v186 offset:17472
	ds_read_b128 v[98:101], v187 offset:26624
	ds_read_b128 v[110:113], v187 offset:26688
	s_waitcnt lgkmcnt(1)
	v_mfma_f32_16x16x32_bf16 v[102:105], v[102:105], v[98:101], 0
	s_waitcnt lgkmcnt(0)
	v_mfma_f32_16x16x32_bf16 v[98:101], v[106:109], v[110:113], v[102:105]
.Lp4n_end_B:
	s_waitcnt lgkmcnt(0)
	s_barrier
	s_cmp_lt_u32 s99, 63
	s_cbranch_scc0 .Lp4n_exit
	s_add_u32 s99, s99, 1
	s_xor_b32 s52, s52, 1
	s_mov_b32 s41, s42
	s_mov_b32 s42, s43
	s_mov_b32 s43, s44
	s_branch .Lp4n_top_A
.Lp4n_exit:
	v_readlane_b32 s10, v250, 0
	v_readlane_b32 s11, v250, 1
	s_load_dwordx2 s[64:65], s[10:11], 0xc8
	s_branch .LBB0_736

	.amdhsa_kernel _Z14fwd_megakernel6Params
		.amdhsa_group_segment_fixed_size 0
		.amdhsa_private_segment_fixed_size 0
		.amdhsa_kernarg_size 464
		.amdhsa_user_sgpr_count 2
		.amdhsa_user_sgpr_dispatch_ptr 0
		.amdhsa_user_sgpr_queue_ptr 0
		.amdhsa_user_sgpr_kernarg_segment_ptr 1
		.amdhsa_user_sgpr_dispatch_id 0
		.amdhsa_user_sgpr_kernarg_preload_length 0
		.amdhsa_user_sgpr_kernarg_preload_offset 0
		.amdhsa_user_sgpr_private_segment_size 0
		.amdhsa_uses_dynamic_stack 0
		.amdhsa_enable_private_segment 0
		.amdhsa_system_sgpr_workgroup_id_x 1
		.amdhsa_system_sgpr_workgroup_id_y 0
		.amdhsa_system_sgpr_workgroup_id_z 0
		.amdhsa_system_sgpr_workgroup_info 0
		.amdhsa_system_vgpr_workitem_id 0
		.amdhsa_next_free_vgpr 256
		.amdhsa_next_free_sgpr 100
		.amdhsa_accum_offset 256
		.amdhsa_reserve_vcc 1
		.amdhsa_float_round_mode_32 0
		.amdhsa_float_round_mode_16_64 0
		.amdhsa_float_denorm_mode_32 3
		.amdhsa_float_denorm_mode_16_64 3
		.amdhsa_dx10_clamp 1
		.amdhsa_ieee_mode 1
		.amdhsa_fp16_overflow 0
		.amdhsa_tg_split 0
		.amdhsa_exception_fp_ieee_invalid_op 0
		.amdhsa_exception_fp_denorm_src 0
		.amdhsa_exception_fp_ieee_div_zero 0
		.amdhsa_exception_fp_ieee_overflow 0
		.amdhsa_exception_fp_ieee_underflow 0
		.amdhsa_exception_fp_ieee_inexact 0
		.amdhsa_exception_int_div_zero 0
	.end_amdhsa_kernel

amdhsa.kernels:
  - .agpr_count:     0
    .args:
      - .offset:         0
        .size:           208
        .value_kind:     by_value
      - .offset:         208
        .size:           4
        .value_kind:     hidden_block_count_x
      - .offset:         212
        .size:           4
        .value_kind:     hidden_block_count_y
      - .offset:         216
        .size:           4
        .value_kind:     hidden_block_count_z
      - .offset:         220
        .size:           2
        .value_kind:     hidden_group_size_x
      - .offset:         222
        .size:           2
        .value_kind:     hidden_group_size_y
      - .offset:         224
        .size:           2
        .value_kind:     hidden_group_size_z
      - .offset:         226
        .size:           2
        .value_kind:     hidden_remainder_x
      - .offset:         228
        .size:           2
        .value_kind:     hidden_remainder_y
      - .offset:         230
        .size:           2
        .value_kind:     hidden_remainder_z
      - .offset:         248
        .size:           8
        .value_kind:     hidden_global_offset_x
      - .offset:         256
        .size:           8
        .value_kind:     hidden_global_offset_y
      - .offset:         264
        .size:           8
        .value_kind:     hidden_global_offset_z
      - .offset:         272
        .size:           2
        .value_kind:     hidden_grid_dims
      - .offset:         328
        .size:           4
        .value_kind:     hidden_dynamic_lds_size
    .group_segment_fixed_size: 0
    .kernarg_segment_align: 8
    .kernarg_segment_size: 464
    .language:       OpenCL C
    .language_version:
      - 2
      - 0
    .max_flat_workgroup_size: 512
    .name:           _Z14fwd_megakernel6Params
    .private_segment_fixed_size: 0
    .sgpr_count:     106
    .sgpr_spill_count: 59
    .symbol:         _Z14fwd_megakernel6Params.kd
    .uniform_work_group_size: 1
    .uses_dynamic_stack: false
    .vgpr_count:     256
    .vgpr_spill_count: 0
    .wavefront_size: 64
